# ssd_state unit-top counted waits: vmcnt(12..8) instead of vmcnt(4..0), the previous unit's state stores are no longer drained
# speedup vs baseline: 1.0024x; 1.0011x over previous
.LBB0_308:
	s_add_i32 s5, s4, 0xffffff00
	s_lshr_b32 s5, s5, 6
	s_add_i32 s5, s5, 8
	s_ashr_i32 s6, s40, 8
	s_cmpk_lt_i32 s4, 0x100
	s_cselect_b32 s5, s6, s5
	s_cselect_b32 s7, 31, 63
	s_lshl_b32 s5, s5, 4
	s_lshl_b32 s6, s1, 1
	s_or_b32 s5, s5, s6
	s_lshl_b32 s9, s5, 6
	s_and_b32 s4, s7, s4
	s_or_b32 s6, s5, 1
	s_lshl_b32 s8, s5, 5
	s_add_i32 s10, s9, 0xfffff000
	s_cmpk_lt_i32 s5, 0x80
	s_cselect_b32 s5, s8, s10
	s_lshl_b32 s8, s6, 5
	s_addk_i32 s9, 0xf040
	s_cmpk_lt_i32 s6, 0x80
	s_cselect_b32 s6, s8, s9
	s_or_b32 s30, s5, s4
	s_sub_i32 s4, s7, s4
	s_lshr_b32 s8, s1, 2
	s_waitcnt vmcnt(0)
	v_mul_f32_e32 v0, 0x3fb8aa3b, v0
	s_add_i32 s34, s4, s6
	v_exp_f32_e32 v0, v0
	s_add_u32 s41, s66, 0x7400000
	s_addc_u32 s42, s67, 0
	s_mul_i32 s4, s8, 0x1800000
	v_readlane_b32 s6, v253, 41
	v_readlane_b32 s7, v253, 42
	s_add_u32 s4, s6, s4
	s_addc_u32 s5, s7, 0
	s_lshl_b32 s1, s1, 7
	v_mul_f32_e32 v1, 0x3fb8aa3b, v1
	v_xor_b32_e32 v89, 0x80000000, v0
	v_add_u32_e32 v25, s33, v8
	v_lshlrev_b32_e32 v0, 3, v8
	s_and_b32 s1, s1, 0x180
	v_exp_f32_e32 v1, v1
	v_and_b32_e32 v26, 56, v0
	v_add_u32_e32 v0, 0x200, v25
	s_add_u32 s4, s4, s1
	v_ashrrev_i32_e32 v70, 3, v0
	v_ashrrev_i32_e32 v72, 4, v0
	v_add_u32_e32 v0, 0x400, v25
	s_addc_u32 s5, s5, 0
	v_ashrrev_i32_e32 v73, 4, v0
	v_add_u32_e32 v0, 0x600, v25
	s_add_u32 s24, s66, 0x16400000
	v_mov_b32_e32 v45, 0
	v_ashrrev_i32_e32 v69, 3, v25
	v_ashrrev_i32_e32 v71, 4, v25
	v_ashrrev_i32_e32 v74, 4, v0
	v_lshlrev_b32_e32 v44, 1, v26
	s_addc_u32 s25, s67, 0
	s_lshl_b32 s1, s8, 8
	v_lshlrev_b32_e32 v8, 4, v8
	v_xor_b32_e32 v88, 0x80000000, v1
	v_lshl_add_u64 v[0:1], s[4:5], 0, v[44:45]
	v_add_u32_e32 v2, s0, v70
	v_add_u32_e32 v4, s0, v69
	s_add_u32 s4, s24, s1
	v_and_b32_e32 v28, 0xf0, v8
	v_add_u32_e32 v8, s0, v71
	v_add_u32_e32 v10, s0, v72
	v_add_u32_e32 v18, s0, v73
	v_add_u32_e32 v20, s0, v74
	v_ashrrev_i32_e32 v3, 31, v2
	v_ashrrev_i32_e32 v5, 31, v4
	s_addc_u32 s5, s25, 0
	v_mov_b32_e32 v29, v45
	v_ashrrev_i32_e32 v9, 31, v8
	v_ashrrev_i32_e32 v11, 31, v10
	v_ashrrev_i32_e32 v19, 31, v18
	v_ashrrev_i32_e32 v21, 31, v20
	v_lshlrev_b64 v[2:3], 9, v[2:3]
	v_lshlrev_b64 v[4:5], 9, v[4:5]
	v_lshl_add_u64 v[16:17], s[4:5], 0, v[28:29]
	v_lshlrev_b64 v[8:9], 9, v[8:9]
	v_lshlrev_b64 v[10:11], 9, v[10:11]
	v_lshlrev_b64 v[18:19], 9, v[18:19]
	v_lshlrev_b64 v[20:21], 9, v[20:21]
	v_lshl_add_u64 v[2:3], v[0:1], 0, v[2:3]
	v_lshl_add_u64 v[0:1], v[0:1], 0, v[4:5]
	v_lshl_add_u64 v[8:9], v[16:17], 0, v[8:9]
	v_lshl_add_u64 v[12:13], v[16:17], 0, v[10:11]
	v_lshl_add_u64 v[18:19], v[16:17], 0, v[18:19]
	v_lshl_add_u64 v[20:21], v[16:17], 0, v[20:21]
	global_load_dwordx4 v[4:7], v[2:3], off
	s_nop 0
	global_load_dwordx4 v[0:3], v[0:1], off
	s_nop 0
	global_load_dwordx4 v[8:11], v[8:9], off
	s_nop 0
	global_load_dwordx4 v[12:15], v[12:13], off
	s_nop 0
	global_load_dwordx4 v[16:19], v[18:19], off
	s_nop 0
	global_load_dwordx4 v[20:23], v[20:21], off
	v_add_u32_e32 v33, -1, v174
	v_and_b32_e32 v30, 63, v174
	v_cmp_lt_i32_e32 vcc, v33, v246
	v_ashrrev_i32_e32 v31, 4, v24
	s_lshl_b32 s28, s72, 5
	v_cndmask_b32_e32 v33, v33, v174, vcc
	v_cmp_ne_u32_e32 vcc, 63, v30
	v_lshlrev_b32_e32 v75, 2, v33
	v_lshl_add_u64 v[46:47], s[24:25], 0, v[28:29]
	v_addc_co_u32_e32 v33, vcc, 0, v174, vcc
	v_lshlrev_b32_e32 v76, 2, v33
	v_add_u32_e32 v33, -2, v174
	v_cmp_lt_i32_e32 vcc, v33, v246
	s_add_u32 s24, s96, s28
	s_addc_u32 s25, s97, 0
	v_cndmask_b32_e32 v33, v33, v174, vcc
	v_cmp_gt_u32_e32 vcc, 62, v30
	v_lshlrev_b32_e32 v77, 2, v33
	v_bfe_u32 v32, v24, 2, 2
	v_cndmask_b32_e64 v33, 0, 2, vcc
	v_add_lshl_u32 v78, v33, v174, 2
	v_add_u32_e32 v33, -4, v174
	v_cmp_lt_i32_e32 vcc, v33, v246
	v_and_b32_e32 v27, 15, v24
	v_cmp_gt_i32_e64 s[0:1], 1, v24
	v_cndmask_b32_e32 v33, v33, v174, vcc
	v_cmp_gt_u32_e32 vcc, 60, v30
	v_lshlrev_b32_e32 v79, 2, v33
	v_cmp_gt_i32_e64 s[4:5], 63, v24
	v_cndmask_b32_e64 v33, 0, 4, vcc
	v_add_lshl_u32 v80, v33, v174, 2
	v_add_u32_e32 v33, -8, v174
	v_cmp_lt_i32_e32 vcc, v33, v246
	v_cmp_gt_i32_e64 s[6:7], 2, v24
	v_cmp_gt_i32_e64 s[8:9], 62, v24
	v_cndmask_b32_e32 v33, v33, v174, vcc
	v_cmp_gt_u32_e32 vcc, 56, v30
	v_lshlrev_b32_e32 v81, 2, v33
	v_cmp_gt_i32_e64 s[10:11], 4, v24
	v_cndmask_b32_e64 v33, 0, 8, vcc
	v_add_lshl_u32 v82, v33, v174, 2
	v_add_u32_e32 v33, -16, v174
	v_cmp_lt_i32_e32 vcc, v33, v246
	v_cmp_gt_i32_e64 s[12:13], 60, v24
	v_cmp_gt_i32_e64 s[14:15], 8, v24
	v_cndmask_b32_e32 v33, v33, v174, vcc
	v_cmp_gt_u32_e32 vcc, 48, v30
	v_lshlrev_b32_e32 v83, 2, v33
	v_add_u32_e32 v33, 0, v28
	v_cndmask_b32_e64 v30, 0, 16, vcc
	v_add_lshl_u32 v84, v30, v174, 2
	v_subrev_u32_e32 v30, 32, v174
	v_cmp_lt_i32_e32 vcc, v30, v246
	v_lshlrev_b32_e32 v28, 2, v31
	v_ashrrev_i32_e32 v29, 31, v28
	v_cndmask_b32_e32 v30, v30, v174, vcc
	v_lshlrev_b32_e32 v85, 2, v30
	v_mov_b32_e32 v30, 0x80
	v_lshl_or_b32 v86, v174, 2, v30
	v_add_u32_e32 v30, 0, v44
	v_lshl_add_u64 v[48:49], v[28:29], 1, s[24:25]
	s_add_i32 s24, s28, 0
	s_movk_i32 s28, 0x90
	v_cmp_gt_i32_e64 s[16:17], 56, v24
	v_cmp_gt_i32_e64 s[18:19], 16, v24
	v_cmp_gt_i32_e64 s[20:21], 48, v24
	v_cmp_gt_i32_e64 s[22:23], 32, v24
	v_lshl_or_b32 v28, v31, 3, v32
	v_lshlrev_b32_e32 v24, 3, v24
	v_mad_u64_u32 v[52:53], s[36:37], v70, s28, v[30:31]
	s_movk_i32 s31, 0x110
	v_and_b32_e32 v29, 24, v24
	v_lshlrev_b32_e32 v24, 7, v27
	v_mul_lo_u32 v53, v28, s31
	v_mul_lo_u32 v28, v28, s28
	v_add_u32_e32 v90, s24, v29
	v_cmp_eq_u32_e64 s[24:25], 0, v25
	v_mad_u64_u32 v[50:51], s[36:37], v69, s28, v[30:31]
	v_mul_lo_u32 v25, v71, s31
	v_mul_lo_u32 v27, v72, s31
	v_mul_lo_u32 v31, v73, s31
	v_mul_lo_u32 v34, v74, s31
	v_add3_u32 v92, 0, v29, v28
	v_add_u32_e32 v29, 0x2200, v53
	v_or_b32_e32 v28, 0x800, v24
	v_or_b32_e32 v30, 0x1000, v24
	v_or_b32_e32 v32, 0x1800, v24
	v_lshl_add_u32 v87, v68, 2, 0
	v_lshl_add_u32 v91, v69, 2, 0
	v_lshl_add_u32 v51, v70, 2, 0
	v_add_u32_e32 v93, 0x1200, v92
	v_add_u32_e32 v94, 0x2400, v92
	v_add_u32_e32 v95, 0x3600, v92
	v_add_u32_e32 v96, v33, v25
	v_add_u32_e32 v97, v33, v27
	v_add_u32_e32 v98, v33, v31
	v_add_u32_e32 v99, v33, v34
	v_lshlrev_b32_e32 v44, 1, v26
	v_add_u32_e32 v100, v90, v29
	v_lshlrev_b32_e32 v54, 1, v24
	v_lshlrev_b32_e32 v56, 1, v28
	v_lshlrev_b32_e32 v58, 1, v30
	v_lshlrev_b32_e32 v60, 1, v32
	s_waitcnt vmcnt(0)
	s_branch .LBB0_310

.LBB0_312:
	s_waitcnt lgkmcnt(0)
	s_barrier
	ds_read2_b32 v[62:63], v45 offset0:127 offset1:128
	ds_read_b32 v24, v91
	ds_read_b32 v25, v91 offset:1024
	s_waitcnt vmcnt(12)
	v_lshlrev_b32_e32 v28, 16, v0
	v_and_b32_e32 v29, 0xffff0000, v0
	v_lshlrev_b32_e32 v30, 16, v1
	s_waitcnt lgkmcnt(1)
	v_sub_f32_e32 v24, v62, v24
	v_mul_f32_e32 v24, 0x3fb8aa3b, v24
	v_exp_f32_e32 v24, v24
	v_and_b32_e32 v31, 0xffff0000, v1
	v_lshlrev_b32_e32 v34, 16, v2
	v_and_b32_e32 v35, 0xffff0000, v2
	s_waitcnt lgkmcnt(0)
	v_mul_f32_e32 v32, v25, v24
	v_pk_mul_f32 v[24:25], v[32:33], v[28:29] op_sel_hi:[0,1]
	v_pk_mul_f32 v[26:27], v[32:33], v[30:31] op_sel_hi:[0,1]
	v_lshlrev_b32_e32 v36, 16, v3
	v_and_b32_e32 v37, 0xffff0000, v3
	v_cvt_pk_bf16_f32 v24, v24, v25
	v_cvt_pk_bf16_f32 v25, v26, v27
	v_pk_mul_f32 v[26:27], v[32:33], v[34:35] op_sel_hi:[0,1]
	v_pk_mul_f32 v[32:33], v[32:33], v[36:37] op_sel_hi:[0,1]
	v_cvt_pk_bf16_f32 v26, v26, v27
	v_cvt_pk_bf16_f32 v27, v32, v33
	ds_write_b128 v50, v[24:27] offset:2048
	ds_read_b32 v24, v91 offset:512
	ds_read_b32 v25, v91 offset:1536
	s_add_i32 s40, s40, s94
	s_cmpk_gt_i32 s40, 0xbff
	s_cselect_b64 s[36:37], -1, 0
	s_waitcnt lgkmcnt(1)
	v_sub_f32_e32 v24, v63, v24
	v_mul_f32_e32 v24, 0x3fb8aa3b, v24
	v_exp_f32_e32 v24, v24
	s_and_b64 vcc, exec, s[36:37]
	s_waitcnt lgkmcnt(0)
	v_mul_f32_e32 v32, v25, v24
	v_pk_mul_f32 v[24:25], v[32:33], v[28:29] op_sel_hi:[0,1]
	v_pk_mul_f32 v[26:27], v[32:33], v[30:31] op_sel_hi:[0,1]
	v_cvt_pk_bf16_f32 v24, v24, v25
	v_cvt_pk_bf16_f32 v25, v26, v27
	v_pk_mul_f32 v[26:27], v[32:33], v[34:35] op_sel_hi:[0,1]
	v_pk_mul_f32 v[28:29], v[32:33], v[36:37] op_sel_hi:[0,1]
	v_cvt_pk_bf16_f32 v26, v26, v27
	v_cvt_pk_bf16_f32 v27, v28, v29
	ds_write_b128 v50, v[24:27] offset:20480
	ds_read_b32 v24, v51
	ds_read_b32 v25, v51 offset:1024
	v_lshlrev_b32_e32 v30, 16, v4
	v_and_b32_e32 v31, 0xffff0000, v4
	v_lshlrev_b32_e32 v32, 16, v5
	s_waitcnt lgkmcnt(1)
	v_sub_f32_e32 v24, v62, v24
	v_mul_f32_e32 v24, 0x3fb8aa3b, v24
	v_exp_f32_e32 v24, v24
	v_and_b32_e32 v33, 0xffff0000, v5
	v_lshlrev_b32_e32 v34, 16, v6
	v_and_b32_e32 v35, 0xffff0000, v6
	s_waitcnt lgkmcnt(0)
	v_mul_f32_e32 v28, v25, v24
	v_pk_mul_f32 v[24:25], v[28:29], v[30:31] op_sel_hi:[0,1]
	v_pk_mul_f32 v[26:27], v[28:29], v[32:33] op_sel_hi:[0,1]
	v_lshlrev_b32_e32 v36, 16, v7
	v_and_b32_e32 v37, 0xffff0000, v7
	v_cvt_pk_bf16_f32 v24, v24, v25
	v_cvt_pk_bf16_f32 v25, v26, v27
	v_pk_mul_f32 v[26:27], v[28:29], v[34:35] op_sel_hi:[0,1]
	v_pk_mul_f32 v[28:29], v[28:29], v[36:37] op_sel_hi:[0,1]
	v_cvt_pk_bf16_f32 v26, v26, v27
	v_cvt_pk_bf16_f32 v27, v28, v29
	ds_write_b128 v52, v[24:27] offset:2048
	ds_read_b32 v24, v51 offset:512
	ds_read_b32 v25, v51 offset:1536
	s_waitcnt lgkmcnt(1)
	v_sub_f32_e32 v24, v63, v24
	v_mul_f32_e32 v24, 0x3fb8aa3b, v24
	v_exp_f32_e32 v24, v24
	s_waitcnt lgkmcnt(0)
	v_mul_f32_e32 v28, v25, v24
	v_pk_mul_f32 v[24:25], v[28:29], v[30:31] op_sel_hi:[0,1]
	v_pk_mul_f32 v[26:27], v[28:29], v[32:33] op_sel_hi:[0,1]
	v_cvt_pk_bf16_f32 v24, v24, v25
	v_cvt_pk_bf16_f32 v25, v26, v27
	v_pk_mul_f32 v[26:27], v[28:29], v[34:35] op_sel_hi:[0,1]
	v_pk_mul_f32 v[28:29], v[28:29], v[36:37] op_sel_hi:[0,1]
	v_cvt_pk_bf16_f32 v26, v26, v27
	v_cvt_pk_bf16_f32 v27, v28, v29
	ds_write_b128 v52, v[24:27] offset:20480
	s_waitcnt vmcnt(11)
	ds_write_b128 v96, v[8:11] offset:38912
	s_waitcnt vmcnt(10)
	ds_write_b128 v97, v[12:15] offset:38912
	s_waitcnt vmcnt(9)
	ds_write_b128 v98, v[16:19] offset:38912
	s_waitcnt vmcnt(8)
	ds_write_b128 v99, v[20:23] offset:38912
	s_cbranch_vccnz .LBB0_316
	s_and_b32 s35, s40, 7
	s_lshl_b32 s28, s35, 2
	v_readlane_b32 s44, v253, 0
	v_mov_b32_e32 v0, s28
	v_readlane_b32 s56, v253, 12
	v_readlane_b32 s57, v253, 13
	s_nop 4
	global_load_dword v24, v0, s[56:57]
	global_load_dword v25, v0, s[56:57] offset:32
	v_readlane_b32 s45, v253, 1
	v_readlane_b32 s44, v253, 39
	s_ashr_i32 s38, s40, 3
	v_readlane_b32 s45, v253, 40
	s_and_b64 vcc, exec, s[44:45]
	s_lshl_b32 s31, s38, 7
	v_readlane_b32 s46, v253, 2
	v_readlane_b32 s47, v253, 3
	v_readlane_b32 s48, v253, 4
	v_readlane_b32 s49, v253, 5
	v_readlane_b32 s50, v253, 6
	v_readlane_b32 s51, v253, 7
	v_readlane_b32 s52, v253, 8
	v_readlane_b32 s53, v253, 9
	v_readlane_b32 s54, v253, 10
	v_readlane_b32 s55, v253, 11
	v_readlane_b32 s58, v253, 14
	v_readlane_b32 s59, v253, 15
	s_cbranch_vccnz .LBB0_315
	v_add_u32_e32 v0, s31, v68
	v_ashrrev_i32_e32 v1, 31, v0
	v_readlane_b32 s44, v253, 35
	v_lshlrev_b64 v[0:1], 6, v[0:1]
	v_readlane_b32 s45, v253, 36
	s_nop 1
	v_lshl_add_u64 v[0:1], s[44:45], 0, v[0:1]
	v_lshl_add_u64 v[0:1], v[0:1], 0, s[28:29]
	global_load_dword v40, v[0:1], off
	global_load_dword v42, v[0:1], off offset:32
	global_load_dword v41, v[0:1], off offset:64
	global_load_dword v43, v[0:1], off offset:96
